# adds: attention unit epilogue issues its 16 norm-gain loads together with counted waits (stores no longer waited per step)
# speedup vs baseline: 1.0117x; 1.0091x over previous
; __device__ __forceinline__ int crow(int r, int hi) { return (r & 3) + 8 * (r >> 2) + 4 * hi; }
; __device__ __forceinline__ void attn_unit(const bf16* Hb, const bf16* KD, const bf16* VD, bf16* MIX, int row0, int S, int head, int qb, float lam, const float* dng, float kn0, float kn1, LAS unsigned char* lds, int wave_u) {
;     ...
;     if (c == 0) {
;         float ss = 0.f;
; #pragma unroll
;         for (int b = 0; b < 4; ++b)
; #pragma unroll
;             for (int r = 0; r < 16; ++r) { const float v = o[b][r] * rl - X[(qs * 32 + r32e) * XS + 32 * b + crow(r, hhe)]; o[b][r] = v; ss += v * v; }
.LBB0_679:
	s_andn2_b64 vcc, exec, s[34:35]
	s_waitcnt lgkmcnt(0)
	s_barrier
	s_cbranch_vccnz .LBB0_607
	v_or_b32_e32 v68, s70, v79
	s_movk_i32 s0, 0x210
	v_mul_lo_u32 v68, v68, s0
	v_add3_u32 v80, 0, v68, v66
	ds_read_b128 v[68:71], v80
	ds_read_b128 v[72:75], v80 offset:32
	ds_read_b128 v[82:85], v80 offset:288
	s_lshl_b32 s2, s69, 7
	s_lshl_b32 s4, s2, 1
	s_waitcnt lgkmcnt(2)
	v_fma_f32 v68, v50, v0, -v68
	v_fma_f32 v50, v51, v0, -v69
	v_fma_f32 v51, v52, v0, -v70
	v_fma_f32 v53, v53, v0, -v71
	s_waitcnt lgkmcnt(1)
	v_fma_f32 v69, v54, v0, -v72
	v_fma_f32 v55, v55, v0, -v73
	ds_read_b128 v[70:73], v80 offset:64
	v_mul_f32_e32 v81, v50, v50
	v_fmac_f32_e32 v81, v68, v68
	v_fma_f32 v56, v56, v0, -v74
	v_fma_f32 v57, v57, v0, -v75
	s_waitcnt lgkmcnt(0)
	v_fma_f32 v54, v60, v0, -v72
	v_fma_f32 v52, v61, v0, -v73
	ds_read_b128 v[72:75], v80 offset:96
	v_fmac_f32_e32 v81, v51, v51
	v_fmac_f32_e32 v81, v53, v53
	v_fmac_f32_e32 v81, v69, v69
	v_fmac_f32_e32 v81, v55, v55
	v_fmac_f32_e32 v81, v56, v56
	v_fma_f32 v70, v58, v0, -v70
	v_fma_f32 v58, v59, v0, -v71
	s_waitcnt lgkmcnt(0)
	v_fma_f32 v71, v62, v0, -v72
	v_fma_f32 v63, v63, v0, -v73
	v_fma_f32 v62, v64, v0, -v74
	v_fma_f32 v61, v65, v0, -v75
	ds_read_b128 v[72:75], v80 offset:128
	v_fmac_f32_e32 v81, v57, v57
	v_fmac_f32_e32 v81, v70, v70
	v_fmac_f32_e32 v81, v58, v58
	v_fmac_f32_e32 v81, v54, v54
	v_fmac_f32_e32 v81, v52, v52
	s_waitcnt lgkmcnt(0)
	v_fma_f32 v60, v34, v0, -v72
	v_fma_f32 v59, v35, v0, -v73
	v_fma_f32 v35, v36, v0, -v74
	v_fma_f32 v34, v37, v0, -v75
	ds_read_b128 v[72:75], v80 offset:160
	v_fmac_f32_e32 v81, v71, v71
	v_fmac_f32_e32 v81, v63, v63
	v_fmac_f32_e32 v81, v62, v62
	v_fmac_f32_e32 v81, v61, v61
	v_fmac_f32_e32 v81, v60, v60
	s_waitcnt lgkmcnt(0)
	v_fma_f32 v64, v40, v0, -v74
	v_fma_f32 v41, v41, v0, -v75
	ds_read_b128 v[74:77], v80 offset:192
	v_fmac_f32_e32 v81, v59, v59
	v_fmac_f32_e32 v81, v35, v35
	v_fmac_f32_e32 v81, v34, v34
	v_fma_f32 v72, v38, v0, -v72
	v_fmac_f32_e32 v81, v72, v72
	v_fma_f32 v65, v39, v0, -v73
	v_fmac_f32_e32 v81, v65, v65
	s_waitcnt lgkmcnt(0)
	v_fma_f32 v39, v42, v0, -v74
	v_fma_f32 v38, v43, v0, -v75
	v_fma_f32 v37, v44, v0, -v76
	v_fma_f32 v36, v45, v0, -v77
	ds_read_b128 v[74:77], v80 offset:224
	v_fmac_f32_e32 v81, v64, v64
	v_fmac_f32_e32 v81, v41, v41
	v_fmac_f32_e32 v81, v39, v39
	v_fmac_f32_e32 v81, v38, v38
	v_fmac_f32_e32 v81, v37, v37
	s_waitcnt lgkmcnt(0)
	v_fma_f32 v73, v46, v0, -v74
	v_fma_f32 v47, v47, v0, -v75
	v_fma_f32 v45, v48, v0, -v76
	v_fma_f32 v44, v49, v0, -v77
	ds_read_b128 v[74:77], v80 offset:256
	v_fmac_f32_e32 v81, v36, v36
	v_fmac_f32_e32 v81, v73, v73
	v_fmac_f32_e32 v81, v47, v47
	v_fmac_f32_e32 v81, v45, v45
	v_fmac_f32_e32 v81, v44, v44
	s_waitcnt lgkmcnt(0)
	v_fma_f32 v43, v18, v0, -v74
	v_fmac_f32_e32 v81, v43, v43
	v_fma_f32 v42, v19, v0, -v75
	v_fmac_f32_e32 v81, v42, v42
	v_fma_f32 v40, v20, v0, -v76
	v_fma_f32 v75, v22, v0, -v82
	v_fma_f32 v74, v23, v0, -v83
	v_fma_f32 v49, v24, v0, -v84
	v_fma_f32 v48, v25, v0, -v85
	ds_read_b128 v[82:85], v80 offset:352
	v_fmac_f32_e32 v81, v40, v40
	v_fma_f32 v20, v21, v0, -v77
	ds_read_b128 v[22:25], v80 offset:320
	v_fmac_f32_e32 v81, v20, v20
	v_fmac_f32_e32 v81, v75, v75
	v_fmac_f32_e32 v81, v74, v74
	v_fmac_f32_e32 v81, v49, v49
	s_waitcnt lgkmcnt(1)
	v_fma_f32 v78, v30, v0, -v82
	v_fma_f32 v77, v31, v0, -v83
	v_fma_f32 v76, v32, v0, -v84
	v_fma_f32 v33, v33, v0, -v85
	ds_read_b128 v[82:85], v80 offset:384
	v_fmac_f32_e32 v81, v48, v48
	s_waitcnt lgkmcnt(1)
	v_fma_f32 v46, v26, v0, -v22
	v_fmac_f32_e32 v81, v46, v46
	v_fma_f32 v26, v27, v0, -v23
	v_fmac_f32_e32 v81, v26, v26
	v_fma_f32 v23, v28, v0, -v24
	v_fmac_f32_e32 v81, v23, v23
	v_fma_f32 v22, v29, v0, -v25
	v_fmac_f32_e32 v81, v22, v22
	s_waitcnt lgkmcnt(0)
	v_fma_f32 v32, v2, v0, -v82
	v_fma_f32 v31, v3, v0, -v83
	v_fma_f32 v29, v4, v0, -v84
	v_fma_f32 v27, v5, v0, -v85
	ds_read_b128 v[2:5], v80 offset:416
	v_fmac_f32_e32 v81, v78, v78
	v_fmac_f32_e32 v81, v77, v77
	v_fmac_f32_e32 v81, v76, v76
	v_fmac_f32_e32 v81, v33, v33
	v_fmac_f32_e32 v81, v32, v32
	s_waitcnt lgkmcnt(0)
	v_fma_f32 v30, v6, v0, -v2
	v_fma_f32 v28, v7, v0, -v3
	v_fma_f32 v25, v8, v0, -v4
	v_fma_f32 v24, v9, v0, -v5
	ds_read_b128 v[2:5], v80 offset:448
	v_fmac_f32_e32 v81, v31, v31
	v_fmac_f32_e32 v81, v29, v29
	v_fmac_f32_e32 v81, v27, v27
	v_fmac_f32_e32 v81, v30, v30
	v_fmac_f32_e32 v81, v28, v28
	s_waitcnt lgkmcnt(0)
	v_fma_f32 v21, v10, v0, -v2
	v_fma_f32 v19, v11, v0, -v3
	v_fma_f32 v18, v12, v0, -v4
	v_fma_f32 v13, v13, v0, -v5
	ds_read_b128 v[2:5], v80 offset:480
	v_fmac_f32_e32 v81, v25, v25
	v_fmac_f32_e32 v81, v24, v24
	v_fmac_f32_e32 v81, v21, v21
	v_fmac_f32_e32 v81, v19, v19
	v_fmac_f32_e32 v81, v18, v18
	s_waitcnt lgkmcnt(0)
	v_pk_fma_f32 v[8:9], v[14:15], v[0:1], v[2:3] op_sel_hi:[1,0,1] neg_lo:[0,0,1] neg_hi:[0,0,1]
	v_fmac_f32_e32 v81, v13, v13
	v_pk_mul_f32 v[2:3], v[8:9], v[8:9]
	v_pk_fma_f32 v[6:7], v[16:17], v[0:1], v[4:5] op_sel_hi:[1,0,1] neg_lo:[0,0,1] neg_hi:[0,0,1]
	v_add_f32_e32 v2, v81, v2
	v_add_f32_e32 v10, v2, v3
	v_pk_mul_f32 v[2:3], v[6:7], v[6:7]
	s_nop 0
	v_add_f32_e32 v0, v10, v2
	v_add_f32_e32 v0, v0, v3
	ds_bpermute_b32 v2, v208, v0
	s_waitcnt lgkmcnt(0)
; __device__ __forceinline__ unsigned cvt_pk_bf16(float lo, float hi) { unsigned r; asm volatile("v_cvt_pk_bf16_f32 %0, %1, %2" : "=v"(r) : "v"(lo), "v"(hi)); return r; }
; __device__ __forceinline__ int crow(int r, int hi) { return (r & 3) + 8 * (r >> 2) + 4 * hi; }
; __device__ __forceinline__ void attn_unit(const bf16* Hb, const bf16* KD, const bf16* VD, bf16* MIX, int row0, int S, int head, int qb, float lam, const float* dng, float kn0, float kn1, LAS unsigned char* lds, int wave_u) {
;     ...
;             for (int r = 0; r < 16; ++r) { const float v = o[b][r] * rl - X[(qs * 32 + r32e) * XS + 32 * b + crow(r, hhe)]; o[b][r] = v; ss += v * v; }
;         ss += __shfl_xor(ss, 32);
;         const float rn = (1.f - LAM_INIT) / sqrtf(ss * (1.f / 128.f) + 1e-5f);
;         bf16* orow = MIX + (size_t)(row0 + q0 + r32e) * D + head * 128;
; #pragma unroll
;         for (int b = 0; b < 4; ++b)
; #pragma unroll
;             for (int rg = 0; rg < 4; ++rg) { const int d = 32 * b + 8 * rg + 4 * hhe; const f32x4 g4 = *(const f32x4*)(dng + d);
;                 u32x2 w; w.x = cvt_pk_bf16(o[b][4 * rg + 0] * rn * g4.x, o[b][4 * rg + 1] * rn * g4.y); w.y = cvt_pk_bf16(o[b][4 * rg + 2] * rn * g4.z, o[b][4 * rg + 3] * rn * g4.w);
;                 *(u32x2*)(orow + d) = w; }
	v_add_f32_e32 v0, v0, v2
	v_fmamk_f32 v0, v0, 0x3c000000, v203
	v_cmp_gt_f32_e32 vcc, s50, v0
	v_mul_f32_e32 v2, 0x4f800000, v0
	s_nop 0
	v_cndmask_b32_e32 v0, v0, v2, vcc
	v_sqrt_f32_e32 v2, v0
	s_nop 0
	v_add_u32_e32 v3, -1, v2
	v_fma_f32 v4, -v3, v2, v0
	v_cmp_ge_f32_e64 s[0:1], 0, v4
	v_add_u32_e32 v4, 1, v2
	s_nop 0
	v_cndmask_b32_e64 v3, v2, v3, s[0:1]
	v_fma_f32 v2, -v4, v2, v0
	v_cmp_lt_f32_e64 s[0:1], 0, v2
	s_nop 1
	v_cndmask_b32_e64 v2, v3, v4, s[0:1]
	v_mul_f32_e32 v3, 0x37800000, v2
	v_cndmask_b32_e32 v2, v2, v3, vcc
	v_cmp_class_f32_e32 vcc, v0, v201
	s_nop 1
	v_cndmask_b32_e32 v0, v2, v0, vcc
	v_div_scale_f32 v2, s[0:1], v0, v0, s61
	v_rcp_f32_e32 v3, v2
	v_readlane_b32 s0, v253, 21
	v_readlane_b32 s1, v253, 22
	v_fma_f32 v4, -v2, v3, 1.0
	v_fmac_f32_e32 v3, v4, v3
	v_div_scale_f32 v4, vcc, s61, v0, s61
	v_mul_f32_e32 v5, v4, v3
	v_fma_f32 v10, -v2, v5, v4
	v_fmac_f32_e32 v5, v10, v3
	v_fma_f32 v2, -v2, v5, v4
	v_div_fmas_f32 v2, v2, v3, v5
	v_div_fixup_f32 v12, v2, v0, s61
	v_add_lshl_u32 v0, v79, s68, 11
	v_readlane_b32 s68, v251, 54
	v_lshl_add_u64 v[2:3], s[0:1], 0, v[0:1]
	v_readlane_b32 s69, v251, 55
	v_lshl_add_u64 v[10:11], v[2:3], 0, s[4:5]
	v_mul_f32_e32 v0, v68, v12
	v_readlane_b32 s70, v251, 56
	v_readlane_b32 s71, v251, 57
	v_readlane_b32 s72, v251, 58
	global_load_dwordx4 v[120:123], v66, s[68:69]
	global_load_dwordx4 v[124:127], v66, s[68:69] offset:32
	global_load_dwordx4 v[128:131], v66, s[68:69] offset:64
	global_load_dwordx4 v[132:135], v66, s[68:69] offset:96
	global_load_dwordx4 v[136:139], v66, s[68:69] offset:128
	global_load_dwordx4 v[140:143], v66, s[68:69] offset:160
	global_load_dwordx4 v[144:147], v66, s[68:69] offset:192
	global_load_dwordx4 v[148:151], v66, s[68:69] offset:224
	global_load_dwordx4 v[152:155], v66, s[68:69] offset:256
	global_load_dwordx4 v[156:159], v66, s[68:69] offset:288
	global_load_dwordx4 v[160:163], v66, s[68:69] offset:320
	global_load_dwordx4 v[164:167], v66, s[68:69] offset:352
	global_load_dwordx4 v[168:171], v66, s[68:69] offset:384
	global_load_dwordx4 v[172:175], v66, s[68:69] offset:416
	global_load_dwordx4 v[176:179], v66, s[68:69] offset:448
	global_load_dwordx4 v[180:183], v66, s[68:69] offset:480
	v_readlane_b32 s73, v251, 59
	v_readlane_b32 s74, v251, 60
	v_readlane_b32 s75, v251, 61
	v_readlane_b32 s76, v251, 62
	v_readlane_b32 s77, v251, 63
	v_readlane_b32 s78, v252, 0
	v_readlane_b32 s79, v252, 1
	v_readlane_b32 s80, v252, 2
	v_readlane_b32 s81, v252, 3
	v_readlane_b32 s82, v252, 4
	v_readlane_b32 s83, v252, 5
	s_waitcnt vmcnt(15)
	v_mul_f32_e32 v0, v120, v0
	v_mul_f32_e32 v2, v50, v12
	v_mul_f32_e32 v2, v121, v2
	v_cvt_pk_bf16_f32 v14, v0, v2
	v_mul_f32_e32 v0, v51, v12
	v_mul_f32_e32 v0, v122, v0
	v_mul_f32_e32 v2, v53, v12
	v_mul_f32_e32 v2, v123, v2
	v_cvt_pk_bf16_f32 v15, v0, v2
	v_lshlrev_b32_e32 v0, 3, v67
	v_lshl_add_u64 v[2:3], v[10:11], 0, v[0:1]
	global_store_dwordx2 v[2:3], v[14:15], off
	v_mul_f32_e32 v0, v69, v12
	v_mul_f32_e32 v4, v55, v12
	v_mul_f32_e32 v5, v57, v12
	s_waitcnt vmcnt(15)
	v_mul_f32_e32 v0, v124, v0
	v_mul_f32_e32 v4, v125, v4
	v_cvt_pk_bf16_f32 v4, v0, v4
	v_mul_f32_e32 v0, v56, v12
	v_mul_f32_e32 v5, v127, v5
	v_mul_f32_e32 v0, v126, v0
	v_cvt_pk_bf16_f32 v5, v0, v5
	global_store_dwordx2 v[2:3], v[4:5], off offset:16
	v_mul_f32_e32 v0, v70, v12
	v_mul_f32_e32 v4, v58, v12
	v_mul_f32_e32 v5, v52, v12
	s_waitcnt vmcnt(15)
	v_mul_f32_e32 v0, v0, v128
	v_mul_f32_e32 v4, v4, v129
	v_cvt_pk_bf16_f32 v4, v0, v4
	v_mul_f32_e32 v0, v54, v12
	v_mul_f32_e32 v5, v5, v131
	v_mul_f32_e32 v0, v0, v130
	v_cvt_pk_bf16_f32 v5, v0, v5
	global_store_dwordx2 v[2:3], v[4:5], off offset:32
	v_mul_f32_e32 v0, v71, v12
	v_mul_f32_e32 v4, v63, v12
	v_mul_f32_e32 v5, v61, v12
	s_waitcnt vmcnt(15)
	v_mul_f32_e32 v0, v0, v132
	v_mul_f32_e32 v4, v4, v133
	v_cvt_pk_bf16_f32 v4, v0, v4
	v_mul_f32_e32 v0, v62, v12
	v_mul_f32_e32 v5, v5, v135
	v_mul_f32_e32 v0, v0, v134
	v_cvt_pk_bf16_f32 v5, v0, v5
	global_store_dwordx2 v[2:3], v[4:5], off offset:48
	v_mul_f32_e32 v0, v60, v12
	v_mul_f32_e32 v4, v59, v12
	v_mul_f32_e32 v5, v34, v12
	s_waitcnt vmcnt(15)
; __device__ __forceinline__ unsigned cvt_pk_bf16(float lo, float hi) { unsigned r; asm volatile("v_cvt_pk_bf16_f32 %0, %1, %2" : "=v"(r) : "v"(lo), "v"(hi)); return r; }
; __device__ __forceinline__ void attn_unit(const bf16* Hb, const bf16* KD, const bf16* VD, bf16* MIX, int row0, int S, int head, int qb, float lam, const float* dng, float kn0, float kn1, LAS unsigned char* lds, int wave_u) {
;     ...
; #pragma unroll
;         for (int b = 0; b < 4; ++b)
; #pragma unroll
;             for (int rg = 0; rg < 4; ++rg) { const int d = 32 * b + 8 * rg + 4 * hhe; const f32x4 g4 = *(const f32x4*)(dng + d);
;                 u32x2 w; w.x = cvt_pk_bf16(o[b][4 * rg + 0] * rn * g4.x, o[b][4 * rg + 1] * rn * g4.y); w.y = cvt_pk_bf16(o[b][4 * rg + 2] * rn * g4.z, o[b][4 * rg + 3] * rn * g4.w);
;                 *(u32x2*)(orow + d) = w; }
	v_mul_f32_e32 v0, v0, v136
	v_mul_f32_e32 v4, v4, v137
	v_cvt_pk_bf16_f32 v4, v0, v4
	v_mul_f32_e32 v0, v35, v12
	v_mul_f32_e32 v5, v5, v139
	v_mul_f32_e32 v0, v0, v138
	v_cvt_pk_bf16_f32 v5, v0, v5
	global_store_dwordx2 v[2:3], v[4:5], off offset:64
	v_mul_f32_e32 v0, v72, v12
	v_mul_f32_e32 v4, v65, v12
	v_mul_f32_e32 v5, v41, v12
	s_waitcnt vmcnt(15)
	v_mul_f32_e32 v0, v0, v140
	v_mul_f32_e32 v4, v4, v141
	v_cvt_pk_bf16_f32 v4, v0, v4
	v_mul_f32_e32 v0, v64, v12
	v_mul_f32_e32 v5, v5, v143
	v_mul_f32_e32 v0, v0, v142
	v_cvt_pk_bf16_f32 v5, v0, v5
	global_store_dwordx2 v[2:3], v[4:5], off offset:80
	v_mul_f32_e32 v0, v39, v12
	v_mul_f32_e32 v4, v38, v12
	v_mul_f32_e32 v5, v36, v12
	s_waitcnt vmcnt(15)
	v_mul_f32_e32 v0, v0, v144
	v_mul_f32_e32 v4, v4, v145
	v_cvt_pk_bf16_f32 v4, v0, v4
	v_mul_f32_e32 v0, v37, v12
	v_mul_f32_e32 v5, v5, v147
	v_mul_f32_e32 v0, v0, v146
	v_cvt_pk_bf16_f32 v5, v0, v5
	global_store_dwordx2 v[2:3], v[4:5], off offset:96
	v_mul_f32_e32 v0, v73, v12
	v_mul_f32_e32 v4, v47, v12
	v_mul_f32_e32 v5, v44, v12
	s_waitcnt vmcnt(15)
	v_mul_f32_e32 v0, v0, v148
	v_mul_f32_e32 v4, v4, v149
	v_cvt_pk_bf16_f32 v4, v0, v4
	v_mul_f32_e32 v0, v45, v12
	v_mul_f32_e32 v5, v5, v151
	v_mul_f32_e32 v0, v0, v150
	v_cvt_pk_bf16_f32 v5, v0, v5
	global_store_dwordx2 v[2:3], v[4:5], off offset:112
	v_mul_f32_e32 v0, v43, v12
	v_mul_f32_e32 v4, v42, v12
	v_mul_f32_e32 v5, v20, v12
	s_waitcnt vmcnt(15)
	v_mul_f32_e32 v0, v0, v152
	v_mul_f32_e32 v4, v4, v153
	v_cvt_pk_bf16_f32 v4, v0, v4
	v_mul_f32_e32 v0, v40, v12
	v_mul_f32_e32 v5, v5, v155
	v_mul_f32_e32 v0, v0, v154
	v_cvt_pk_bf16_f32 v5, v0, v5
	global_store_dwordx2 v[2:3], v[4:5], off offset:128
	v_mul_f32_e32 v0, v75, v12
	v_mul_f32_e32 v4, v74, v12
	v_mul_f32_e32 v5, v48, v12
	s_waitcnt vmcnt(15)
	v_mul_f32_e32 v0, v0, v156
	v_mul_f32_e32 v4, v4, v157
	v_cvt_pk_bf16_f32 v4, v0, v4
	v_mul_f32_e32 v0, v49, v12
	v_mul_f32_e32 v5, v5, v159
	v_mul_f32_e32 v0, v0, v158
	v_cvt_pk_bf16_f32 v5, v0, v5
	global_store_dwordx2 v[2:3], v[4:5], off offset:144
	v_mul_f32_e32 v0, v46, v12
	v_mul_f32_e32 v4, v26, v12
	v_mul_f32_e32 v5, v22, v12
	s_waitcnt vmcnt(15)
	v_mul_f32_e32 v0, v0, v160
	v_mul_f32_e32 v4, v4, v161
	v_cvt_pk_bf16_f32 v4, v0, v4
	v_mul_f32_e32 v0, v23, v12
	v_mul_f32_e32 v5, v5, v163
	v_mul_f32_e32 v0, v0, v162
	v_cvt_pk_bf16_f32 v5, v0, v5
	global_store_dwordx2 v[2:3], v[4:5], off offset:160
	v_mul_f32_e32 v0, v78, v12
	v_mul_f32_e32 v4, v77, v12
	v_mul_f32_e32 v5, v33, v12
	s_waitcnt vmcnt(15)
	v_mul_f32_e32 v0, v0, v164
	v_mul_f32_e32 v4, v4, v165
	v_cvt_pk_bf16_f32 v4, v0, v4
	v_mul_f32_e32 v0, v76, v12
	v_mul_f32_e32 v5, v5, v167
	v_mul_f32_e32 v0, v0, v166
	v_cvt_pk_bf16_f32 v5, v0, v5
	global_store_dwordx2 v[2:3], v[4:5], off offset:176
	v_mul_f32_e32 v0, v32, v12
	v_mul_f32_e32 v4, v31, v12
	v_mul_f32_e32 v5, v27, v12
	s_waitcnt vmcnt(15)
	v_mul_f32_e32 v0, v0, v168
	v_mul_f32_e32 v4, v4, v169
	v_cvt_pk_bf16_f32 v4, v0, v4
	v_mul_f32_e32 v0, v29, v12
	v_mul_f32_e32 v5, v5, v171
	v_mul_f32_e32 v0, v0, v170
	v_cvt_pk_bf16_f32 v5, v0, v5
	global_store_dwordx2 v[2:3], v[4:5], off offset:192
	v_mul_f32_e32 v0, v30, v12
	v_mul_f32_e32 v4, v28, v12
	v_mul_f32_e32 v5, v24, v12
	s_waitcnt vmcnt(15)
	v_mul_f32_e32 v0, v0, v172
	v_mul_f32_e32 v4, v4, v173
	v_cvt_pk_bf16_f32 v4, v0, v4
	v_mul_f32_e32 v0, v25, v12
	v_mul_f32_e32 v5, v5, v175
	v_mul_f32_e32 v0, v0, v174
	v_cvt_pk_bf16_f32 v5, v0, v5
	global_store_dwordx2 v[2:3], v[4:5], off offset:208
	v_mul_f32_e32 v0, v21, v12
	v_mul_f32_e32 v4, v19, v12
	v_mul_f32_e32 v5, v13, v12
	s_waitcnt vmcnt(15)
	v_mul_f32_e32 v0, v0, v176
	v_mul_f32_e32 v4, v4, v177
	v_cvt_pk_bf16_f32 v4, v0, v4
	v_mul_f32_e32 v0, v18, v12
	v_mul_f32_e32 v5, v5, v179
	v_mul_f32_e32 v0, v0, v178
	v_cvt_pk_bf16_f32 v5, v0, v5
	global_store_dwordx2 v[2:3], v[4:5], off offset:224
	v_mul_f32_e32 v0, v8, v12
	v_mul_f32_e32 v4, v9, v12
	v_mul_f32_e32 v5, v7, v12
	s_waitcnt vmcnt(15)
	v_mul_f32_e32 v0, v0, v180
	v_mul_f32_e32 v4, v4, v181
	v_cvt_pk_bf16_f32 v4, v0, v4
	v_mul_f32_e32 v0, v6, v12
	v_mul_f32_e32 v5, v5, v183
	v_mul_f32_e32 v0, v0, v182
	v_cvt_pk_bf16_f32 v5, v0, v5
	global_store_dwordx2 v[2:3], v[4:5], off offset:240
	s_branch .LBB0_607
